# static s_setprio 1 for waves 4-7 during both scan phases (on top of v014)
# baseline (speedup 1.0000x reference)
.LBB0_814:
	s_or_b64 exec, exec, s[0:1]
	s_cmp_gt_i32 s2, 63
	s_cselect_b64 s[96:97], -1, 0
	s_cmpk_lt_u32 s2, 0xc0
	s_cselect_b64 s[0:1], -1, 0
	v_writelane_b32 v254, s0, 22
	s_cmpk_gt_u32 s2, 0xbf
	s_mov_b32 s93, 0
	v_writelane_b32 v254, s1, 23
	s_cselect_b64 s[0:1], -1, 0
	v_writelane_b32 v254, s0, 24
	s_cmpk_gt_u32 s2, 0x5f
	v_mov_b32_e32 v2, 0
	v_writelane_b32 v254, s1, 25
	s_cselect_b64 s[0:1], -1, 0
	v_writelane_b32 v254, s0, 26
	s_cmpk_lt_u32 s2, 0x60
	s_movk_i32 s89, 0x1800
	v_writelane_b32 v254, s1, 27
	s_cselect_b64 s[0:1], -1, 0
	v_writelane_b32 v254, s0, 28
	s_movk_i32 s71, 0x80
	s_mov_b32 s69, 0xc2a00000
	v_writelane_b32 v254, s1, 29
	s_add_i32 s0, s2, 0xffffffa0
	v_writelane_b32 v254, s0, 30
	s_lshl_b32 s0, s2, 1
	s_add_i32 s1, s0, 0xfffffee1
	s_addk_i32 s0, 0xfee0
	v_writelane_b32 v254, s1, 31
	s_cmpk_lt_u32 s2, 0xe0
	v_writelane_b32 v254, s0, 32
	s_cselect_b64 s[0:1], -1, 0
	s_add_i32 s3, s2, 32
	v_writelane_b32 v254, s3, 33
	s_add_i32 s3, s2, 64
	v_writelane_b32 v254, s3, 34
	s_sub_i32 s3, s2, 64
	v_writelane_b32 v254, s3, 35
	s_ashr_i32 s3, s2, 1
	v_writelane_b32 v254, s3, 36
	s_and_b32 s3, s2, 1
	v_writelane_b32 v254, s3, 37
	s_add_u32 s3, s24, 0x2d23000
	v_writelane_b32 v254, s3, 38
	s_addc_u32 s3, s25, 0
	v_writelane_b32 v254, s3, 39
	s_add_u32 s3, s24, 0x2d22400
	v_writelane_b32 v254, s3, 40
	s_addc_u32 s3, s25, 0
	v_writelane_b32 v254, s3, 41
	s_add_u32 s3, s24, 0x2d22c00
	v_writelane_b32 v254, s3, 42
	s_addc_u32 s3, s25, 0
	v_writelane_b32 v254, s3, 43
	s_add_u32 s3, s24, 0x2d22e00
	v_writelane_b32 v254, s3, 44
	s_addc_u32 s3, s25, 0
	v_writelane_b32 v254, s3, 45
	s_add_u32 s3, s22, 0x3000000
	v_writelane_b32 v254, s3, 46
	s_addc_u32 s3, s23, 0
	v_writelane_b32 v254, s3, 47
	s_add_u32 s3, s22, 0x4000000
	v_writelane_b32 v254, s3, 48
	s_addc_u32 s3, s23, 0
	v_writelane_b32 v254, s3, 49
	s_add_u32 s3, s24, 0x7522000
	v_writelane_b32 v254, s3, 50
	s_addc_u32 s3, s25, 0
	s_cmp_eq_u64 s[40:41], 0
	v_writelane_b32 v254, s3, 51
	s_cselect_b64 s[94:95], -1, 0
	s_xor_b64 s[0:1], s[0:1], -1
	v_writelane_b32 v254, s0, 52
	s_add_i32 s88, 0, 0x11400
	s_add_i32 s72, 0, 0x11600
	v_writelane_b32 v254, s1, 53
	s_add_i32 s0, 0, 0x11700
	v_writelane_b32 v254, s0, 54
	s_add_i32 s0, 0, 0x11740
	v_writelane_b32 v254, s0, 55
	s_add_i32 s0, 0, 0x11780
	v_writelane_b32 v254, s0, 56
	s_add_i32 s0, 0, 0x117c0
	v_writelane_b32 v254, s0, 57
	s_add_i32 s0, 0, 0x11500
	v_writelane_b32 v254, s0, 58
	s_add_i32 s0, 0, 0x11540
	v_writelane_b32 v254, s0, 59
	s_add_i32 s0, 0, 0x11580
	v_writelane_b32 v254, s0, 60
	s_add_i32 s0, 0, 0x115c0
	v_writelane_b32 v254, s0, 61
	s_add_i32 s75, 0, 0x11640
	v_readlane_b32 s78, v254, 19
	v_readlane_b32 s79, v254, 20
	v_writelane_b32 v254, s96, 62
	s_add_i32 s18, 0, 0x11680
	s_add_i32 s19, 0, 0x116c0
	s_add_i32 s70, 0, 0x11440
	s_add_i32 s29, 0, 0x11480
	s_add_i32 s68, 0, 0x114c0
	v_mov_b32_e32 v188, 0x7c
	v_mov_b32_e32 v189, 0x42a00000
	s_mov_b32 s90, 0
	v_writelane_b32 v254, s97, 63
	s_waitcnt lgkmcnt(0)
	s_barrier
	v_readfirstlane_b32 s98, v224
	s_nop 0
	s_lshr_b32 s98, s98, 8
	s_cbranch_scc0 .Lprio_skip0
	s_setprio 1
.Lprio_skip0:
	s_branch .LBB0_818

.LBB0_935:
	s_setprio 0
	s_waitcnt vmcnt(0)
	s_barrier
	s_mov_b64 s[0:1], exec
	v_readlane_b32 s4, v254, 9
	v_readlane_b32 s5, v254, 10
	s_and_b64 s[4:5], s[0:1], s[4:5]
	s_xor_b64 s[0:1], s[4:5], s[0:1]
	s_mov_b64 exec, s[4:5]
	s_cbranch_execz .LBB0_989
	s_add_i32 s3, 0, 0x20000
	v_mov_b32_e32 v0, s3
	s_waitcnt vmcnt(0) expcnt(0) lgkmcnt(0)
	ds_read_b32 v2, v0
	s_add_i32 s3, 0, 0x20004
	v_mov_b32_e32 v0, s3
	ds_read_b32 v0, v0
	s_waitcnt lgkmcnt(1)
	v_cmp_ne_u32_e32 vcc, 0, v2
	s_cbranch_vccnz .LBB0_952
	s_add_u32 s4, s24, 0xed22200
	s_addc_u32 s5, s25, 0
	s_add_u32 s10, s24, 0xed22400
	s_addc_u32 s11, s25, 0
	s_add_u32 s12, s24, 0xed22500
	s_addc_u32 s13, s25, 0
	s_add_u32 s40, s24, 0xed22600
	s_addc_u32 s41, s25, 0
	s_add_u32 s42, s24, 0xed22700
	s_addc_u32 s43, s25, 0
	s_add_u32 s46, s24, 0xed22800
	s_addc_u32 s47, s25, 0
	s_add_u32 s48, s24, 0xed22900
	s_addc_u32 s49, s25, 0
	s_add_u32 s52, s24, 0xed22a00
	s_addc_u32 s53, s25, 0
	s_add_u32 s56, s24, 0xed22b00
	s_addc_u32 s57, s25, 0
	s_add_u32 s62, s24, 0xed22c00
	s_addc_u32 s63, s25, 0
	s_add_u32 s66, s24, 0xed22d00
	s_addc_u32 s67, s25, 0
	s_add_u32 s68, s24, 0xed22e00
	s_addc_u32 s69, s25, 0
	s_add_u32 s74, s24, 0xed22f00
	s_addc_u32 s75, s25, 0
	s_add_u32 s80, s24, 0xed23000
	s_addc_u32 s81, s25, 0
	s_add_u32 s82, s24, 0xed23100
	s_addc_u32 s83, s25, 0
	s_add_u32 s84, s24, 0xed23200
	v_readlane_b32 s3, v254, 8
	s_addc_u32 s85, s25, 0
	s_mul_i32 s3, s27, s3
	s_add_u32 s86, s24, 0xed23300
	s_mul_i32 s3, s3, s26
	s_addc_u32 s87, s25, 0
	s_mov_b32 s19, 1
	v_mov_b32_e32 v16, 0
	s_branch .LBB0_940

.LBB0_1353:
	s_or_b64 exec, exec, s[0:1]
	s_add_i32 s3, s2, 0xc0
	s_add_i32 s16, s2, 0x180
	s_add_u32 s17, s24, 0x2d22800
	s_addc_u32 s19, s25, 0
	s_add_u32 s28, s22, 0x4800000
	s_addc_u32 s29, s23, 0
	s_mov_b32 s35, 0
	s_movk_i32 s48, 0x400
	s_mov_b32 s49, 0xbfb8aa3b
	s_mov_b32 s50, 0x800000
	s_mov_b32 s51, 0x3f317217
	s_mov_b32 s52, 0x7f800000
	s_mov_b32 s53, 0xbd22000
	v_mov_b32_e32 v2, 0
	s_movk_i32 s54, 0x110
	v_mov_b32_e32 v172, 0x41b17218
	s_waitcnt lgkmcnt(0)
	s_barrier
	v_readfirstlane_b32 s98, v224
	s_nop 0
	s_lshr_b32 s98, s98, 8
	s_cbranch_scc0 .Lprio_skip1
	s_setprio 1

.LBB0_1373:
	s_setprio 0
	s_waitcnt vmcnt(0)
	s_barrier
	s_mov_b64 s[0:1], exec
	v_readlane_b32 s4, v254, 9
	v_readlane_b32 s5, v254, 10
	s_and_b64 s[4:5], s[0:1], s[4:5]
	s_xor_b64 s[0:1], s[4:5], s[0:1]
	s_mov_b64 exec, s[4:5]
	s_cbranch_execz .LBB0_1426
	s_add_i32 s3, 0, 0x20000
	v_mov_b32_e32 v0, s3
	s_waitcnt vmcnt(0) expcnt(0) lgkmcnt(0)
	ds_read_b32 v2, v0
	s_add_i32 s3, 0, 0x20004
	v_mov_b32_e32 v0, s3
	ds_read_b32 v0, v0
	s_waitcnt lgkmcnt(1)
	v_cmp_ne_u32_e32 vcc, 0, v2
	s_cbranch_vccnz .LBB0_1389
	s_add_u32 s4, s24, 0xed22200
	s_addc_u32 s5, s25, 0
	s_add_u32 s6, s24, 0xed22400
	s_addc_u32 s7, s25, 0
	s_add_u32 s14, s24, 0xed22500
	s_addc_u32 s15, s25, 0
	s_add_u32 s36, s24, 0xed22600
	s_addc_u32 s37, s25, 0
	s_add_u32 s38, s24, 0xed22700
	s_addc_u32 s39, s25, 0
	s_add_u32 s40, s24, 0xed22800
	s_addc_u32 s41, s25, 0
	s_add_u32 s42, s24, 0xed22900
	s_addc_u32 s43, s25, 0
	s_add_u32 s44, s24, 0xed22a00
	s_addc_u32 s45, s25, 0
	s_add_u32 s46, s24, 0xed22b00
	s_addc_u32 s47, s25, 0
	s_add_u32 s48, s24, 0xed22c00
	s_addc_u32 s49, s25, 0
	s_add_u32 s50, s24, 0xed22d00
	s_addc_u32 s51, s25, 0
	s_add_u32 s52, s24, 0xed22e00
	s_addc_u32 s53, s25, 0
	s_add_u32 s54, s24, 0xed22f00
	s_addc_u32 s55, s25, 0
	s_add_u32 s56, s24, 0xed23000
	s_addc_u32 s57, s25, 0
	s_add_u32 s58, s24, 0xed23100
	s_addc_u32 s59, s25, 0
	s_add_u32 s62, s24, 0xed23200
	v_readlane_b32 s3, v254, 8
	s_addc_u32 s63, s25, 0
	s_mul_i32 s3, s27, s3
	s_add_u32 s64, s24, 0xed23300
	s_mul_i32 s3, s3, s26
	s_addc_u32 s65, s25, 0
	s_mov_b32 s19, 1
	v_mov_b32_e32 v16, 0
	s_branch .LBB0_1377

	.amdhsa_kernel _Z14fwd_megakernel6Params
		.amdhsa_group_segment_fixed_size 0
		.amdhsa_private_segment_fixed_size 0
		.amdhsa_kernarg_size 440
		.amdhsa_user_sgpr_count 2
		.amdhsa_user_sgpr_dispatch_ptr 0
		.amdhsa_user_sgpr_queue_ptr 0
		.amdhsa_user_sgpr_kernarg_segment_ptr 1
		.amdhsa_user_sgpr_dispatch_id 0
		.amdhsa_user_sgpr_kernarg_preload_length 0
		.amdhsa_user_sgpr_kernarg_preload_offset 0
		.amdhsa_user_sgpr_private_segment_size 0
		.amdhsa_uses_dynamic_stack 0
		.amdhsa_enable_private_segment 0
		.amdhsa_system_sgpr_workgroup_id_x 1
		.amdhsa_system_sgpr_workgroup_id_y 0
		.amdhsa_system_sgpr_workgroup_id_z 0
		.amdhsa_system_sgpr_workgroup_info 0
		.amdhsa_system_vgpr_workitem_id 2
		.amdhsa_next_free_vgpr 256
		.amdhsa_next_free_sgpr 102
		.amdhsa_accum_offset 256
		.amdhsa_reserve_vcc 1
		.amdhsa_float_round_mode_32 0
		.amdhsa_float_round_mode_16_64 0
		.amdhsa_float_denorm_mode_32 3
		.amdhsa_float_denorm_mode_16_64 3
		.amdhsa_dx10_clamp 1
		.amdhsa_ieee_mode 1
		.amdhsa_fp16_overflow 0
		.amdhsa_tg_split 0
		.amdhsa_exception_fp_ieee_invalid_op 0
		.amdhsa_exception_fp_denorm_src 0
		.amdhsa_exception_fp_ieee_div_zero 0
		.amdhsa_exception_fp_ieee_overflow 0
		.amdhsa_exception_fp_ieee_underflow 0
		.amdhsa_exception_fp_ieee_inexact 0
		.amdhsa_exception_int_div_zero 0
	.end_amdhsa_kernel

amdhsa.kernels:
  - .agpr_count:     0
    .args:
      - .offset:         0
        .size:           184
        .value_kind:     by_value
      - .offset:         184
        .size:           4
        .value_kind:     hidden_block_count_x
      - .offset:         188
        .size:           4
        .value_kind:     hidden_block_count_y
      - .offset:         192
        .size:           4
        .value_kind:     hidden_block_count_z
      - .offset:         196
        .size:           2
        .value_kind:     hidden_group_size_x
      - .offset:         198
        .size:           2
        .value_kind:     hidden_group_size_y
      - .offset:         200
        .size:           2
        .value_kind:     hidden_group_size_z
      - .offset:         202
        .size:           2
        .value_kind:     hidden_remainder_x
      - .offset:         204
        .size:           2
        .value_kind:     hidden_remainder_y
      - .offset:         206
        .size:           2
        .value_kind:     hidden_remainder_z
      - .offset:         224
        .size:           8
        .value_kind:     hidden_global_offset_x
      - .offset:         232
        .size:           8
        .value_kind:     hidden_global_offset_y
      - .offset:         240
        .size:           8
        .value_kind:     hidden_global_offset_z
      - .offset:         248
        .size:           2
        .value_kind:     hidden_grid_dims
      - .offset:         272
        .size:           8
        .value_kind:     hidden_multigrid_sync_arg
      - .offset:         304
        .size:           4
        .value_kind:     hidden_dynamic_lds_size
    .group_segment_fixed_size: 0
    .kernarg_segment_align: 8
    .kernarg_segment_size: 440
    .language:       OpenCL C
    .language_version:
      - 2
      - 0
    .max_flat_workgroup_size: 512
    .name:           _Z14fwd_megakernel6Params
    .private_segment_fixed_size: 0
    .sgpr_count:     108
    .sgpr_spill_count: 76
    .symbol:         _Z14fwd_megakernel6Params.kd
    .uniform_work_group_size: 1
    .uses_dynamic_stack: false
    .vgpr_count:     256
    .vgpr_spill_count: 0
    .wavefront_size: 64
